# v74: v68 with 16 expert-index buckets per token in the gather order (was 8)
# speedup vs baseline: 1.0049x; 1.0049x over previous
.LBB0_869:
	ds_read2st64_b32 v[4:5], v220 offset0:12 offset1:13
	ds_read2st64_b32 v[6:7], v220 offset0:14 offset1:15
	v_mov_b32_e32 v10, 0
	v_mov_b32_e32 v11, 0
	s_mov_b32 s0, 0
	s_waitcnt lgkmcnt(0)
	v_lshrrev_b32_e32 v8, 10, v4
	v_lshrrev_b32_e32 v9, 10, v5
	v_cmp_eq_u32_e64 s[42:43], 0, v8
	v_cmp_eq_u32_e64 s[100:101], 0, v9
	s_bcnt1_i32_b64 s1, s[42:43]
	s_bcnt1_i32_b64 s41, s[100:101]
	v_mbcnt_lo_u32_b32 v12, s42, 0
	v_mbcnt_hi_u32_b32 v12, s43, v12
	v_mbcnt_lo_u32_b32 v13, s100, 0
	v_mbcnt_hi_u32_b32 v13, s101, v13
	s_add_i32 s98, s0, s1
	v_add_u32_e32 v12, s0, v12
	v_add_u32_e32 v13, s98, v13
	v_cndmask_b32_e64 v10, v10, v12, s[42:43]
	v_cndmask_b32_e64 v11, v11, v13, s[100:101]
	s_add_i32 s0, s98, s41
	v_cmp_eq_u32_e64 s[42:43], 1, v8
	v_cmp_eq_u32_e64 s[100:101], 1, v9
	s_bcnt1_i32_b64 s1, s[42:43]
	s_bcnt1_i32_b64 s41, s[100:101]
	v_mbcnt_lo_u32_b32 v12, s42, 0
	v_mbcnt_hi_u32_b32 v12, s43, v12
	v_mbcnt_lo_u32_b32 v13, s100, 0
	v_mbcnt_hi_u32_b32 v13, s101, v13
	s_add_i32 s98, s0, s1
	v_add_u32_e32 v12, s0, v12
	v_add_u32_e32 v13, s98, v13
	v_cndmask_b32_e64 v10, v10, v12, s[42:43]
	v_cndmask_b32_e64 v11, v11, v13, s[100:101]
	s_add_i32 s0, s98, s41
	v_cmp_eq_u32_e64 s[42:43], 2, v8
	v_cmp_eq_u32_e64 s[100:101], 2, v9
	s_bcnt1_i32_b64 s1, s[42:43]
	s_bcnt1_i32_b64 s41, s[100:101]
	v_mbcnt_lo_u32_b32 v12, s42, 0
	v_mbcnt_hi_u32_b32 v12, s43, v12
	v_mbcnt_lo_u32_b32 v13, s100, 0
	v_mbcnt_hi_u32_b32 v13, s101, v13
	s_add_i32 s98, s0, s1
	v_add_u32_e32 v12, s0, v12
	v_add_u32_e32 v13, s98, v13
	v_cndmask_b32_e64 v10, v10, v12, s[42:43]
	v_cndmask_b32_e64 v11, v11, v13, s[100:101]
	s_add_i32 s0, s98, s41
	v_cmp_eq_u32_e64 s[42:43], 3, v8
	v_cmp_eq_u32_e64 s[100:101], 3, v9
	s_bcnt1_i32_b64 s1, s[42:43]
	s_bcnt1_i32_b64 s41, s[100:101]
	v_mbcnt_lo_u32_b32 v12, s42, 0
	v_mbcnt_hi_u32_b32 v12, s43, v12
	v_mbcnt_lo_u32_b32 v13, s100, 0
	v_mbcnt_hi_u32_b32 v13, s101, v13
	s_add_i32 s98, s0, s1
	v_add_u32_e32 v12, s0, v12
	v_add_u32_e32 v13, s98, v13
	v_cndmask_b32_e64 v10, v10, v12, s[42:43]
	v_cndmask_b32_e64 v11, v11, v13, s[100:101]
	s_add_i32 s0, s98, s41
	v_cmp_eq_u32_e64 s[42:43], 4, v8
	v_cmp_eq_u32_e64 s[100:101], 4, v9
	s_bcnt1_i32_b64 s1, s[42:43]
	s_bcnt1_i32_b64 s41, s[100:101]
	v_mbcnt_lo_u32_b32 v12, s42, 0
	v_mbcnt_hi_u32_b32 v12, s43, v12
	v_mbcnt_lo_u32_b32 v13, s100, 0
	v_mbcnt_hi_u32_b32 v13, s101, v13
	s_add_i32 s98, s0, s1
	v_add_u32_e32 v12, s0, v12
	v_add_u32_e32 v13, s98, v13
	v_cndmask_b32_e64 v10, v10, v12, s[42:43]
	v_cndmask_b32_e64 v11, v11, v13, s[100:101]
	s_add_i32 s0, s98, s41
	v_cmp_eq_u32_e64 s[42:43], 5, v8
	v_cmp_eq_u32_e64 s[100:101], 5, v9
	s_bcnt1_i32_b64 s1, s[42:43]
	s_bcnt1_i32_b64 s41, s[100:101]
	v_mbcnt_lo_u32_b32 v12, s42, 0
	v_mbcnt_hi_u32_b32 v12, s43, v12
	v_mbcnt_lo_u32_b32 v13, s100, 0
	v_mbcnt_hi_u32_b32 v13, s101, v13
	s_add_i32 s98, s0, s1
	v_add_u32_e32 v12, s0, v12
	v_add_u32_e32 v13, s98, v13
	v_cndmask_b32_e64 v10, v10, v12, s[42:43]
	v_cndmask_b32_e64 v11, v11, v13, s[100:101]
	s_add_i32 s0, s98, s41
	v_cmp_eq_u32_e64 s[42:43], 6, v8
	v_cmp_eq_u32_e64 s[100:101], 6, v9
	s_bcnt1_i32_b64 s1, s[42:43]
	s_bcnt1_i32_b64 s41, s[100:101]
	v_mbcnt_lo_u32_b32 v12, s42, 0
	v_mbcnt_hi_u32_b32 v12, s43, v12
	v_mbcnt_lo_u32_b32 v13, s100, 0
	v_mbcnt_hi_u32_b32 v13, s101, v13
	s_add_i32 s98, s0, s1
	v_add_u32_e32 v12, s0, v12
	v_add_u32_e32 v13, s98, v13
	v_cndmask_b32_e64 v10, v10, v12, s[42:43]
	v_cndmask_b32_e64 v11, v11, v13, s[100:101]
	s_add_i32 s0, s98, s41
	v_cmp_eq_u32_e64 s[42:43], 7, v8
	v_cmp_eq_u32_e64 s[100:101], 7, v9
	s_bcnt1_i32_b64 s1, s[42:43]
	s_bcnt1_i32_b64 s41, s[100:101]
	v_mbcnt_lo_u32_b32 v12, s42, 0
	v_mbcnt_hi_u32_b32 v12, s43, v12
	v_mbcnt_lo_u32_b32 v13, s100, 0
	v_mbcnt_hi_u32_b32 v13, s101, v13
	s_add_i32 s98, s0, s1
	v_add_u32_e32 v12, s0, v12
	v_add_u32_e32 v13, s98, v13
	v_cndmask_b32_e64 v10, v10, v12, s[42:43]
	v_cndmask_b32_e64 v11, v11, v13, s[100:101]
	s_add_i32 s0, s98, s41
	v_cmp_eq_u32_e64 s[42:43], 8, v8
	v_cmp_eq_u32_e64 s[100:101], 8, v9
	s_bcnt1_i32_b64 s1, s[42:43]
	s_bcnt1_i32_b64 s41, s[100:101]
	v_mbcnt_lo_u32_b32 v12, s42, 0
	v_mbcnt_hi_u32_b32 v12, s43, v12
	v_mbcnt_lo_u32_b32 v13, s100, 0
	v_mbcnt_hi_u32_b32 v13, s101, v13
	s_add_i32 s98, s0, s1
	v_add_u32_e32 v12, s0, v12
	v_add_u32_e32 v13, s98, v13
	v_cndmask_b32_e64 v10, v10, v12, s[42:43]
	v_cndmask_b32_e64 v11, v11, v13, s[100:101]
	s_add_i32 s0, s98, s41
	v_cmp_eq_u32_e64 s[42:43], 9, v8
	v_cmp_eq_u32_e64 s[100:101], 9, v9
	s_bcnt1_i32_b64 s1, s[42:43]
	s_bcnt1_i32_b64 s41, s[100:101]
	v_mbcnt_lo_u32_b32 v12, s42, 0
	v_mbcnt_hi_u32_b32 v12, s43, v12
	v_mbcnt_lo_u32_b32 v13, s100, 0
	v_mbcnt_hi_u32_b32 v13, s101, v13
	s_add_i32 s98, s0, s1
	v_add_u32_e32 v12, s0, v12
	v_add_u32_e32 v13, s98, v13
	v_cndmask_b32_e64 v10, v10, v12, s[42:43]
	v_cndmask_b32_e64 v11, v11, v13, s[100:101]
	s_add_i32 s0, s98, s41
	v_cmp_eq_u32_e64 s[42:43], 10, v8
	v_cmp_eq_u32_e64 s[100:101], 10, v9
	s_bcnt1_i32_b64 s1, s[42:43]
	s_bcnt1_i32_b64 s41, s[100:101]
	v_mbcnt_lo_u32_b32 v12, s42, 0
	v_mbcnt_hi_u32_b32 v12, s43, v12
	v_mbcnt_lo_u32_b32 v13, s100, 0
	v_mbcnt_hi_u32_b32 v13, s101, v13
	s_add_i32 s98, s0, s1
	v_add_u32_e32 v12, s0, v12
	v_add_u32_e32 v13, s98, v13
	v_cndmask_b32_e64 v10, v10, v12, s[42:43]
	v_cndmask_b32_e64 v11, v11, v13, s[100:101]
	s_add_i32 s0, s98, s41
	v_cmp_eq_u32_e64 s[42:43], 11, v8
	v_cmp_eq_u32_e64 s[100:101], 11, v9
	s_bcnt1_i32_b64 s1, s[42:43]
	s_bcnt1_i32_b64 s41, s[100:101]
	v_mbcnt_lo_u32_b32 v12, s42, 0
	v_mbcnt_hi_u32_b32 v12, s43, v12
	v_mbcnt_lo_u32_b32 v13, s100, 0
	v_mbcnt_hi_u32_b32 v13, s101, v13
	s_add_i32 s98, s0, s1
	v_add_u32_e32 v12, s0, v12
	v_add_u32_e32 v13, s98, v13
	v_cndmask_b32_e64 v10, v10, v12, s[42:43]
	v_cndmask_b32_e64 v11, v11, v13, s[100:101]
	s_add_i32 s0, s98, s41
	v_cmp_eq_u32_e64 s[42:43], 12, v8
	v_cmp_eq_u32_e64 s[100:101], 12, v9
	s_bcnt1_i32_b64 s1, s[42:43]
	s_bcnt1_i32_b64 s41, s[100:101]
	v_mbcnt_lo_u32_b32 v12, s42, 0
	v_mbcnt_hi_u32_b32 v12, s43, v12
	v_mbcnt_lo_u32_b32 v13, s100, 0
	v_mbcnt_hi_u32_b32 v13, s101, v13
	s_add_i32 s98, s0, s1
	v_add_u32_e32 v12, s0, v12
	v_add_u32_e32 v13, s98, v13
	v_cndmask_b32_e64 v10, v10, v12, s[42:43]
	v_cndmask_b32_e64 v11, v11, v13, s[100:101]
	s_add_i32 s0, s98, s41
	v_cmp_eq_u32_e64 s[42:43], 13, v8
	v_cmp_eq_u32_e64 s[100:101], 13, v9
	s_bcnt1_i32_b64 s1, s[42:43]
	s_bcnt1_i32_b64 s41, s[100:101]
	v_mbcnt_lo_u32_b32 v12, s42, 0
	v_mbcnt_hi_u32_b32 v12, s43, v12
	v_mbcnt_lo_u32_b32 v13, s100, 0
	v_mbcnt_hi_u32_b32 v13, s101, v13
	s_add_i32 s98, s0, s1
	v_add_u32_e32 v12, s0, v12
	v_add_u32_e32 v13, s98, v13
	v_cndmask_b32_e64 v10, v10, v12, s[42:43]
	v_cndmask_b32_e64 v11, v11, v13, s[100:101]
	s_add_i32 s0, s98, s41
	v_cmp_eq_u32_e64 s[42:43], 14, v8
	v_cmp_eq_u32_e64 s[100:101], 14, v9
	s_bcnt1_i32_b64 s1, s[42:43]
	s_bcnt1_i32_b64 s41, s[100:101]
	v_mbcnt_lo_u32_b32 v12, s42, 0
	v_mbcnt_hi_u32_b32 v12, s43, v12
	v_mbcnt_lo_u32_b32 v13, s100, 0
	v_mbcnt_hi_u32_b32 v13, s101, v13
	s_add_i32 s98, s0, s1
	v_add_u32_e32 v12, s0, v12
	v_add_u32_e32 v13, s98, v13
	v_cndmask_b32_e64 v10, v10, v12, s[42:43]
	v_cndmask_b32_e64 v11, v11, v13, s[100:101]
	s_add_i32 s0, s98, s41
	v_cmp_eq_u32_e64 s[42:43], 15, v8
	v_cmp_eq_u32_e64 s[100:101], 15, v9
	s_bcnt1_i32_b64 s1, s[42:43]
	s_bcnt1_i32_b64 s41, s[100:101]
	v_mbcnt_lo_u32_b32 v12, s42, 0
	v_mbcnt_hi_u32_b32 v12, s43, v12
	v_mbcnt_lo_u32_b32 v13, s100, 0
	v_mbcnt_hi_u32_b32 v13, s101, v13
	s_add_i32 s98, s0, s1
	v_add_u32_e32 v12, s0, v12
	v_add_u32_e32 v13, s98, v13
	v_cndmask_b32_e64 v10, v10, v12, s[42:43]
	v_cndmask_b32_e64 v11, v11, v13, s[100:101]
	s_add_i32 s0, s98, s41
	s_and_b32 s1, s19, 1
	s_mul_i32 s1, s1, 0x7f
	v_xor_b32_e32 v10, s1, v10
	v_xor_b32_e32 v11, s1, v11
	v_lshl_add_u32 v10, v10, 2, v199
	v_lshl_add_u32 v11, v11, 2, v199
	ds_write_b32 v10, v4
	ds_write_b32 v11, v5
	ds_write_b32 v10, v6 offset:512
	ds_write_b32 v11, v7 offset:512
	v_add_u32_e32 v0, s48, v0
	v_cmp_gt_i32_e32 vcc, s52, v0
	v_mov_b32_e32 v2, s49
	v_mov_b32_e32 v3, s50
	v_cndmask_b32_e32 v2, v2, v3, vcc
	v_add_u32_e32 v152, v0, v2
	v_ashrrev_i32_e32 v153, 31, v152
	v_lshlrev_b64 v[2:3], 11, v[152:153]
	v_lshl_add_u64 v[2:3], v[138:139], 0, v[2:3]
	global_load_dwordx2 v[4:5], v[2:3], off
	global_load_dwordx2 v[6:7], v[2:3], off offset:512
	global_load_dwordx2 v[10:11], v[2:3], off offset:1024
	global_load_dwordx2 v[12:13], v[2:3], off offset:1536
	s_lshl_b32 s0, s19, 10
	v_add3_u32 v9, v131, s0, v136
	ds_read2st64_b32 v[14:15], v220 offset0:12 offset1:13
	ds_read2st64_b32 v[16:17], v220 offset0:14 offset1:15
	v_mov_b32_e32 v184, 0
	s_mov_b32 s1, 0
	v_mov_b32_e32 v185, v184
	v_mov_b32_e32 v186, v184
	v_mov_b32_e32 v187, v184
	v_mov_b32_e32 v182, v184
	v_mov_b32_e32 v183, v184
	v_mov_b32_e32 v180, v184
	v_mov_b32_e32 v181, v184
	v_mov_b32_e32 v178, v184
	v_mov_b32_e32 v179, v184
	v_mov_b32_e32 v176, v184
	v_mov_b32_e32 v177, v184
	v_mov_b32_e32 v174, v184
	v_mov_b32_e32 v175, v184
	v_mov_b32_e32 v172, v184
	v_mov_b32_e32 v173, v184
	s_waitcnt lgkmcnt(0)
	v_mov_b32_e32 v0, v14
	v_lshlrev_b64 v[18:19], 2, v[0:1]
	v_lshl_add_u64 v[20:21], s[34:35], 0, v[18:19]
	v_lshl_add_u64 v[18:19], s[90:91], 0, v[18:19]
	global_load_dword v8, v[20:21], off
	global_load_dword v22, v[18:19], off
	v_mov_b32_e32 v0, v15
	v_lshlrev_b64 v[18:19], 2, v[0:1]
	v_lshl_add_u64 v[20:21], s[34:35], 0, v[18:19]
	v_lshl_add_u64 v[18:19], s[90:91], 0, v[18:19]
	global_load_dword v23, v[20:21], off
	global_load_dword v24, v[18:19], off
	s_waitcnt vmcnt(0)
	v_lshlrev_b32_e32 v154, 16, v4
	v_and_b32_e32 v155, 0xffff0000, v4
	v_lshlrev_b32_e32 v156, 16, v5
	v_and_b32_e32 v157, 0xffff0000, v5
	v_lshlrev_b32_e32 v158, 16, v6
	v_and_b32_e32 v159, 0xffff0000, v6
	v_lshlrev_b32_e32 v162, 16, v7
	v_and_b32_e32 v163, 0xffff0000, v7
	v_lshlrev_b32_e32 v164, 16, v10
	v_and_b32_e32 v165, 0xffff0000, v10
	v_lshlrev_b32_e32 v166, 16, v11
	v_and_b32_e32 v167, 0xffff0000, v11
	v_lshlrev_b32_e32 v168, 16, v12
	v_and_b32_e32 v169, 0xffff0000, v12
	v_lshlrev_b32_e32 v170, 16, v13
	v_and_b32_e32 v171, 0xffff0000, v13
	v_mul_f32_e32 v6, v16, v22
	v_mul_f32_e32 v0, v17, v24
	ds_write2st64_b32 v9, v8, v23 offset1:1
	ds_write2st64_b32 v9, v6, v0 offset0:2 offset1:3
	v_readlane_b32 s98, v254, 28
	s_nop 0
	s_bitcmp1_b32 s98, 0
	s_cbranch_scc1 .Lprio_base_one
	s_setprio 0
	s_branch .Lprio_base_done
